# mixer phases rebalanced: 64 window-attention items run at the head of the phase-1 queue; phase 2 starts mLSTM items on half the workgroups and attention on the other half
# speedup vs baseline: 1.0060x; 1.0058x over previous
; template <int MODE>
; DI void attn_mfma(const Params& p, int l, int b, int hd, int qb, unsigned char* smem) {
;     ...
;     const float lam_init = 0.8f - 0.6f * __expf(-0.3f * (float)l);
; DI void ph_mixers1(const Params& p_in, int l, unsigned char* smem, volatile lds_int* slot) {
;   const int nfill = (l == 0) ? WT_TILES / 8 : 0;
;   const int total = 64 + 1152 + 576 + 576 + nfill;
;   unsigned* ctr = (unsigned*)(p_in.ws + WS_CTL + 13824) + (l * 2 + 0);
;   for (;;) {
;     const int it = next_item(ctr, slot);
;     if (it >= total) break;
.LBB0_424:
	v_writelane_b32 v254, s68, 21
	s_andn2_b64 vcc, exec, s[0:1]
	s_nop 0
	v_writelane_b32 v254, s69, 22
	s_cbranch_vccnz .LBB0_801
	s_and_b64 s[0:1], s[72:73], exec
	s_movk_i32 s0, 0x9ec
	s_cselect_b32 s15, s0, 0x940
	s_addk_i32 s15, 0x40
	s_mov_b32 s101, 0
	s_lshl_b32 s2, s48, 2
	v_writelane_b32 v252, s2, 3
	s_lshl_b32 s2, s48, 1
	s_lshl_b64 s[0:1], s[2:3], 2
	s_add_u32 s0, s68, s0
	v_cvt_f32_u32_e32 v0, s48
	s_addc_u32 s1, s69, s1
	s_add_u32 s0, s0, 0xfc89600
	s_addc_u32 s1, s1, 0
	v_writelane_b32 v254, s0, 23
	s_lshl_b32 s2, s48, 7
	v_readlane_b32 s72, v253, 23
	v_mul_f32_e32 v0, 0xbe99999a, v0
	v_writelane_b32 v254, s1, 24
	s_lshl_b32 s0, s48, 6
	s_lshl_b64 s[4:5], s[2:3], 2
	v_readlane_b32 s74, v253, 25
	v_mul_f32_e32 v0, 0x3fb8aa3b, v0
	s_mov_b32 s1, s3
	v_readlane_b32 s73, v253, 24
	v_readlane_b32 s75, v253, 26
	s_add_u32 s4, s74, s4
	v_exp_f32_e32 v0, v0
	v_readlane_b32 s76, v253, 27
	v_readlane_b32 s72, v254, 15
	s_addc_u32 s5, s75, s5
	s_lshl_b64 s[0:1], s[0:1], 2
	v_readlane_b32 s77, v253, 28
	v_readlane_b32 s73, v254, 16
	v_writelane_b32 v254, s4, 25
	s_add_u32 s0, s76, s0
	s_addc_u32 s1, s77, s1
	v_writelane_b32 v254, s5, 26
	v_writelane_b32 v254, s0, 27
	v_fmamk_f32 v168, v0, 0xbf19999a, v175
	v_sub_f32_e32 v169, 1.0, v168
	v_writelane_b32 v254, s1, 28
	v_writelane_b32 v254, s15, 29
	v_readlane_b32 s78, v253, 29
	v_readlane_b32 s79, v253, 30
	v_readlane_b32 s80, v253, 31
	v_readlane_b32 s81, v253, 32
	v_readlane_b32 s82, v253, 33
	v_readlane_b32 s83, v253, 34
	v_readlane_b32 s84, v253, 35
	v_readlane_b32 s85, v253, 36
	v_readlane_b32 s86, v253, 37
	v_readlane_b32 s87, v253, 38
	s_branch .LBB0_429

; template <int MX>
; DI RecRaw rec_load(const Params& p, int b, int h, int dir, int T0, int tid) {
;   const bf16_t* P = (const bf16_t*)(p.ws + WS_P);
;   const int tt = tid >> 2, k0 = (tid & 3) * 16;
;   const size_t row = (size_t)b * NTOK + T0 + tt;
;   const bf16_t* rp = P + row * PW;
;   RecRaw w;
;   if (MX == 0) {
;     const int fcol = (dir ? B_FB : B_FF) + h * 64 + k0;
;     w.a0 = *(const uint4*)(rp + fcol); w.a1 = *(const uint4*)(rp + fcol + 8);
;     w.b0 = *(const uint4*)(rp + B_Q + h * 64 + k0); w.b1 = *(const uint4*)(rp + B_Q + h * 64 + k0 + 8);
;     w.c0 = *(const uint4*)(rp + B_I + h * 64 + k0); w.c1 = *(const uint4*)(rp + B_I + h * 64 + k0 + 8);
;     w.ig = 0.f; w.fg = 0.f;
;   } else {
;     w.a0 = *(const uint4*)(rp + D_K + h * 64 + k0); w.a1 = *(const uint4*)(rp + D_K + h * 64 + k0 + 8);
;     w.b0 = *(const uint4*)(rp + D_Q + h * 64 + k0); w.b1 = *(const uint4*)(rp + D_Q + h * 64 + k0 + 8);
;     w.c0 = *(const uint4*)(rp + D_V + h * 64 + k0); w.c1 = *(const uint4*)(rp + D_V + h * 64 + k0 + 8);
;     const float* G = (const float*)(p.ws + WS_GATES) + row * 16;
;     w.ig = G[dir * 4 + h]; w.fg = G[8 + dir * 4 + h];
;   }
; DI void ph_mixers1(const Params& p_in, int l, unsigned char* smem, volatile lds_int* slot) {
;     ...
;     const int it = next_item(ctr, slot);
;     if (it >= total) break;
;     Params p = p_in;
;     asm volatile("" : "+s"(p.ws));
;     if (it < 64) {
;       const int mx = it >> 5, h = it & 3, b = (it >> 2) & 7;
;       if (l == 0) { if (mx == 0) rec_output<0>(p, l, b, h, 0, smem); else rec_output<1>(p, l, b, h, 0, smem); }
;     } else if (it < 1216) { const int r = it - 64; const int qb = r % 36, bh = r / 36; if (!(l == 1 && qb < 4)) attn_mfma<0>(p, l, bh >> 2, bh & 3, qb, smem); }
;     else if (it >= 64 + 1152 + 576 + 576) {
;       const int f = it - (64 + 1152 + 576 + 576);
;       const int tid = ltid_w(p.wave);
;       for (int u = 0; u < 8; ++u) wt_tile(p, 1, f * 8 + u, smem, tid);
;     } else {
;       int r = it - 1216; const int mx = r / 576; r %= 576;
;       const int sc = r % 9; r /= 9; const int dir = r & 1, h = (r >> 1) & 3, b = r >> 3;
;       const bool last = dir == 0 ? (sc == 8) : (sc == 1);
;       if (!last) { if (mx == 0) rec_summary<0>(p, l, b, h, dir, sc, smem); else rec_summary<1>(p, l, b, h, dir, sc, smem); }
.LBB0_431:
	s_or_b64 exec, exec, s[0:1]
	s_waitcnt lgkmcnt(0)
	s_barrier
	ds_read_b32 v0, v176
	s_mov_b64 s[0:1], -1
	s_waitcnt lgkmcnt(0)
	v_readfirstlane_b32 s46, v0
	s_cmp_ge_i32 s46, s15
	s_cbranch_scc1 .LBB0_428
	s_cmp_lt_u32 s46, 64
	s_cbranch_scc0 .Lx_m1
	s_addk_i32 s46, 0x400
	s_mov_b32 s27, s46
	s_mov_b32 s101, 1
	s_branch .Lx_attnC
.Lx_m1:
	s_addk_i32 s46, 0xffc0
	s_mov_b64 s[40:41], s[68:69]
	s_cmp_gt_i32 s46, 63
	s_cbranch_scc0 .LBB0_592
	s_cmpk_gt_u32 s46, 0x4bf
	s_cbranch_scc0 .LBB0_575
	s_cmpk_lt_u32 s46, 0x940
	s_cbranch_scc0 .LBB0_567
	s_add_i32 s0, s46, 0xfffffb40
	s_add_i32 s1, s46, 0xfffff900
	s_cmpk_gt_u32 s0, 0x23f
	s_cselect_b64 s[4:5], -1, 0
	s_cmpk_lt_u32 s0, 0x240
	s_cselect_b32 s0, s0, s1
	s_mul_hi_u32 s1, s0, 0x38e38e39
	s_lshr_b32 s48, s1, 1
	s_mul_i32 s2, s48, 9
	s_sub_i32 s47, s0, s2
	s_bfe_u32 s49, s1, 0x10001
	s_bitcmp1_b32 s1, 1
	s_cselect_b64 s[20:21], -1, 0
	s_cmp_eq_u32 s49, 0
	s_cselect_b64 s[0:1], -1, 0
	s_and_b64 s[6:7], s[0:1], exec
	s_cselect_b32 s2, 8, 1
	s_cmp_eq_u32 s47, s2
	s_cbranch_scc1 .LBB0_566
	s_lshr_b32 s2, s48, 3
	s_bfe_u32 s50, s48, 0x20001
	s_mov_b64 s[6:7], -1
	s_and_b64 vcc, exec, s[4:5]
	s_mul_i32 s26, s2, 0x900
	s_cbranch_vccz .LBB0_509
	s_lshl_b32 s51, s47, 8
	v_readlane_b32 s2, v253, 39
	s_and_b64 s[4:5], s[0:1], exec
	s_waitcnt vmcnt(0)
	v_mbcnt_lo_u32_b32 v49, -1, 0
	v_mbcnt_hi_u32_b32 v49, -1, v49
	s_nop 0
	v_or_b32_e32 v48, s2, v49
	s_cselect_b32 s2, 0, 0xc0
	s_add_u32 s28, s40, 0x41c6000
	s_addc_u32 s29, s41, 0
	v_ashrrev_i32_e32 v0, 2, v48
	v_lshlrev_b32_e32 v1, 4, v49
	s_add_i32 s4, s26, s51
	v_and_b32_e32 v2, 48, v1
	s_or_b32 s2, s4, s2
	v_ashrrev_i32_e32 v1, 31, v0
	v_lshl_add_u64 v[4:5], v[0:1], 0, s[2:3]
	v_mov_b64_e32 v[6:7], s[28:29]
	v_mad_u64_u32 v[6:7], s[4:5], v4, s33, v[6:7]
	v_mad_i32_i24 v7, v5, s33, v7
	s_lshl_b32 s2, s50, 7
	v_lshlrev_b32_e32 v160, 1, v2
	v_lshl_add_u64 v[6:7], v[6:7], 0, s[2:3]
	v_lshl_add_u64 v[6:7], v[6:7], 0, v[160:161]
	s_mov_b64 s[4:5], 0x1400
	s_lshl_b32 s22, s50, 6
	v_lshl_add_u64 v[8:9], v[6:7], 0, s[4:5]
	v_add_co_u32_e32 v10, vcc, s16, v6
	s_mov_b64 s[4:5], 0x1600
	s_nop 0
	v_addc_co_u32_e32 v11, vcc, 0, v7, vcc
	v_lshl_add_u64 v[6:7], v[6:7], 0, s[4:5]
	s_add_u32 s4, s40, 0xdb56000
	s_addc_u32 s5, s41, 0
	v_lshlrev_b64 v[4:5], 6, v[4:5]
	s_lshl_b32 s2, s50, 2
	s_lshl_b32 s6, s49, 4
	v_lshl_add_u64 v[4:5], s[4:5], 0, v[4:5]
	s_or_b32 s2, s6, s2
	v_lshl_add_u64 v[4:5], v[4:5], 0, s[2:3]
	s_barrier
	global_load_dwordx4 v[40:43], v[10:11], off offset:1024
	global_load_dwordx4 v[32:35], v[8:9], off offset:16
	global_load_dwordx4 v[44:47], v[10:11], off offset:1536
	global_load_dwordx4 v[36:39], v[6:7], off offset:16
	global_load_dword v52, v[4:5], off
	global_load_dword v53, v[4:5], off offset:32
	v_and_b32_e32 v3, 3, v49
	v_cmp_eq_u32_e64 s[6:7], 0, v3
	v_lshlrev_b32_e32 v56, 11, v3
	v_lshlrev_b32_e32 v3, 1, v0
	v_ashrrev_i32_e32 v4, 1, v48
	s_mov_b32 s27, s3
	s_add_u32 s30, s4, s2
	v_and_or_b32 v3, v3, 14, v56
	v_and_b32_e32 v4, -16, v4
	s_movk_i32 s2, 0x50
	v_lshl_add_u64 v[50:51], v[0:1], 0, s[26:27]
	v_lshlrev_b32_e32 v57, 8, v0
	v_xad_u32 v67, v4, s2, v3
	s_movk_i32 s2, 0x60
	v_and_b32_e32 v58, -16, v0
	v_bfi_b32 v0, -16, v0, v49
	v_bfe_u32 v1, v49, 4, 2
	v_xad_u32 v68, v4, s2, v3
	s_movk_i32 s2, 0x70
	v_lshlrev_b32_e32 v71, 7, v0
	v_lshrrev_b32_e32 v0, 1, v49
	v_and_b32_e32 v55, 63, v49
	v_add_u32_e32 v62, v3, v4
	v_xad_u32 v63, v4, 16, v3
	v_xad_u32 v64, v4, 32, v3
	v_xad_u32 v65, v4, 48, v3
	v_xad_u32 v66, v4, 64, v3
	v_xad_u32 v69, v4, s2, v3
	v_bfe_u32 v3, v49, 1, 3
	v_bitop3_b32 v0, v1, v0, 7 bitop3:0x78
	v_lshlrev_b32_e32 v73, 4, v0
	v_bitop3_b32 v0, v1, v3, 4 bitop3:0x36
	v_cmp_lt_u32_e32 vcc, 1, v55
	v_lshlrev_b32_e32 v74, 4, v0
	s_addc_u32 s31, s5, 0
	v_cndmask_b32_e64 v0, 0, 1, vcc
	v_cmp_gt_u32_e32 vcc, 62, v55
	v_lshlrev_b32_e32 v78, 4, v3
	v_and_b32_e32 v54, 15, v49
	v_cndmask_b32_e64 v1, 0, 1, vcc
	v_cndmask_b32_e64 v0, v1, v0, s[0:1]
	v_and_b32_e32 v0, 1, v0
	v_cmp_lt_u32_e32 vcc, 3, v55
	v_cmp_eq_u32_e64 s[24:25], 1, v0
	s_and_b64 s[4:5], s[0:1], exec
	v_cndmask_b32_e64 v0, 0, 1, vcc
	v_cmp_gt_u32_e32 vcc, 60, v55
	v_lshlrev_b32_e32 v77, 7, v48
	v_xor_b32_e32 v3, 48, v78
	v_cndmask_b32_e64 v1, 0, 1, vcc
	v_cndmask_b32_e64 v0, v1, v0, s[0:1]
	v_and_b32_e32 v0, 1, v0
	v_cmp_lt_u32_e32 vcc, 7, v55
	v_cmp_eq_u32_e64 s[14:15], 1, v0
	v_xor_b32_e32 v4, 64, v78
	v_cndmask_b32_e64 v0, 0, 1, vcc
	v_cmp_gt_u32_e32 vcc, 56, v55
	v_xor_b32_e32 v5, 0x50, v78
	v_xor_b32_e32 v6, 0x60, v78
	v_cndmask_b32_e64 v1, 0, 1, vcc
	v_cndmask_b32_e64 v0, v1, v0, s[0:1]
	v_and_b32_e32 v0, 1, v0
	v_cmp_lt_u32_e32 vcc, 15, v55
	v_cmp_eq_u32_e64 s[44:45], 1, v0
	v_xor_b32_e32 v7, 0x70, v78
	v_cndmask_b32_e64 v0, 0, 1, vcc
	v_cmp_gt_u32_e32 vcc, 48, v55
	v_mov_b32_e32 v61, 0
	s_mov_b32 s52, 2
	v_cndmask_b32_e64 v1, 0, 1, vcc
	v_cndmask_b32_e64 v0, v1, v0, s[0:1]
	v_and_b32_e32 v0, 1, v0
	v_cmp_eq_u32_e64 s[18:19], 1, v0
	v_cmp_gt_u32_e32 vcc, 32, v55
	v_xor_b32_e32 v0, 16, v78
	v_xor_b32_e32 v1, 32, v78
	s_mov_b32 s53, 1
	v_cmp_gt_u32_e64 s[8:9], 64, v48
	s_cselect_b32 s27, 0x3f00, 0
	v_cmp_lt_u32_e64 s[10:11], 3, v48
	v_lshlrev_b32_e32 v60, 6, v48
	v_lshl_or_b32 v70, v54, 2, v187
	v_lshlrev_b32_e32 v72, 7, v54
	v_cmp_gt_i32_e64 s[4:5], 64, v48
	v_lshlrev_b32_e32 v75, 8, v49
	s_xor_b64 s[12:13], s[0:1], vcc
	v_lshl_add_u32 v76, v48, 2, v187
	v_mov_b32_e32 v59, 1.0
	s_lshl_b32 s2, s22, 1
	v_lshlrev_b32_e32 v160, 1, v2
	v_add_u32_e32 v79, v77, v0
	v_add_u32_e32 v80, v77, v1
	v_add_u32_e32 v81, v77, v3
	v_add_u32_e32 v82, v77, v4
	v_add_u32_e32 v83, v77, v5
	v_add_u32_e32 v84, v77, v6
	v_add_u32_e32 v85, v77, v7
	v_mov_b32_e32 v28, 0
	v_mov_b32_e32 v29, v61
	v_mov_b32_e32 v30, v61
	v_mov_b32_e32 v31, v61
	v_mov_b32_e32 v24, 0
	v_mov_b32_e32 v25, v61
	v_mov_b32_e32 v26, v61
	v_mov_b32_e32 v27, v61
	v_mov_b32_e32 v20, 0
	v_mov_b32_e32 v21, v61
	v_mov_b32_e32 v22, v61
	v_mov_b32_e32 v23, v61
	v_mov_b32_e32 v16, 0
	v_mov_b32_e32 v17, v61
	v_mov_b32_e32 v18, v61
	v_mov_b32_e32 v19, v61

; DI void ph_mixers2(const Params& p_in, int l, unsigned char* smem, volatile lds_int* slot) {
;   const int total = 512 + 576;
;   unsigned* ctr = (unsigned*)(p_in.ws + WS_CTL + 13824) + (l * 2 + 1);
;   for (;;) {
;     const int it = next_item(ctr, slot);
;     if (it >= total) break;
;     Params p = p_in;
;     asm volatile("" : "+s"(p.ws));
.LBB0_801:
	s_cmp_le_i32 s58, s28
	s_cselect_b64 s[0:1], -1, 0
	s_cmp_lt_i32 s28, s59
	s_cselect_b64 s[4:5], -1, 0
	s_and_b64 s[0:1], s[0:1], s[4:5]
	s_andn2_b64 vcc, exec, s[0:1]
	s_cbranch_vccnz .LBB0_1050
	s_lshl_b32 s2, s48, 1
	s_lshl_b64 s[0:1], s[2:3], 2
	s_add_u32 s0, s68, s0
	s_addc_u32 s1, s69, s1
	s_add_u32 s0, s0, 0xfc89604
	s_addc_u32 s1, s1, 0
	v_writelane_b32 v252, s0, 1
	s_lshl_b32 s2, s48, 6
	v_readlane_b32 s72, v253, 23
	v_writelane_b32 v252, s1, 2
	s_lshl_b32 s0, s48, 2
	v_writelane_b32 v252, s0, 3
	s_lshl_b64 s[0:1], s[2:3], 2
	v_readlane_b32 s84, v253, 35
	v_readlane_b32 s85, v253, 36
	s_add_u32 s4, s84, s0
	v_readlane_b32 s80, v253, 31
	s_addc_u32 s5, s85, s1
	v_readlane_b32 s81, v253, 32
	v_writelane_b32 v252, s4, 4
	s_add_u32 s0, s80, s0
	s_addc_u32 s1, s81, s1
	v_writelane_b32 v252, s5, 5
	v_writelane_b32 v252, s0, 6
	v_readlane_b32 s73, v253, 24
	v_readlane_b32 s74, v253, 25
	v_readlane_b32 s75, v253, 26
	v_readlane_b32 s76, v253, 27
	v_readlane_b32 s77, v253, 28
	v_readlane_b32 s78, v253, 29
	v_readlane_b32 s79, v253, 30
	v_readlane_b32 s82, v253, 33
	v_readlane_b32 s83, v253, 34
	v_readlane_b32 s86, v253, 37
	v_readlane_b32 s87, v253, 38
	v_writelane_b32 v252, s1, 7
	v_readlane_b32 s98, v253, 43
	s_nop 1
	s_cmpk_eq_i32 s98, 0x200
	s_cselect_b32 s98, 1, 0
	s_mov_b32 s101, 0
	s_mov_b32 s99, s98
	s_branch .LBB0_805
.LBB0_803:
	s_cmp_eq_u32 s101, 1
	s_cbranch_scc0 .Lx_ret2
	s_mov_b32 s101, 0
	v_readlane_b32 s48, v254, 17
	s_nop 3
	v_cvt_f32_u32_e32 v0, s48
	v_mul_f32_e32 v0, 0xbe99999a, v0
	v_mul_f32_e32 v0, 0x3fb8aa3b, v0
	v_exp_f32_e32 v0, v0
	s_nop 0
	v_fmamk_f32 v168, v0, 0xbf19999a, v175
	v_sub_f32_e32 v169, 1.0, v168
	s_branch .LBB0_426

; DI void ph_mixers2(const Params& p_in, int l, unsigned char* smem, volatile lds_int* slot) {
;   const int total = 512 + 576;
;   unsigned* ctr = (unsigned*)(p_in.ws + WS_CTL + 13824) + (l * 2 + 1);
;   for (;;) {
;     const int it = next_item(ctr, slot);
;     if (it >= total) break;
.LBB0_805:
	s_waitcnt lgkmcnt(0)
	s_barrier
	s_cmp_eq_u32 s98, 1
	s_cbranch_scc0 .Lm2_dyn
	s_mov_b32 s98, 0
	v_readlane_b32 s27, v253, 42
	s_nop 1
	s_cmp_lt_u32 s27, 0x100
	s_cselect_b32 s0, 0x200, 0
	s_add_i32 s27, s27, s0
	v_mov_b32_e32 v0, s27
	s_movk_i32 s0, 0x3ff
	s_branch .Lm2_have

; DI int next_item(unsigned* ctr, volatile lds_int* slot) {
;   __syncthreads();
;   if (threadIdx.x == 0) *slot = (int)__hip_atomic_fetch_add(ctr, 1u, __ATOMIC_RELAXED, __HIP_MEMORY_SCOPE_AGENT);
;   __syncthreads();
;   return *slot;
; DI void ph_mixers2(const Params& p_in, int l, unsigned char* smem, volatile lds_int* slot) {
;     ...
;   unsigned* ctr = (unsigned*)(p_in.ws + WS_CTL + 13824) + (l * 2 + 1);
;   for (;;) {
;     const int it = next_item(ctr, slot);
.LBB0_807:
	s_or_b64 exec, exec, s[0:1]
	s_waitcnt lgkmcnt(0)
	s_barrier
	ds_read_b32 v0, v176
	s_movk_i32 s0, 0x3ff
	s_waitcnt lgkmcnt(0)
	s_cmp_eq_u32 s99, 1
	s_cbranch_scc0 .Lm2_have
	v_readfirstlane_b32 s27, v0
	s_nop 1
	s_cmp_lt_u32 s27, 0x100
	s_cselect_b32 s1, 0, 2
	s_lshl_b32 s1, s1, 8
	s_add_i32 s27, s27, s1
	v_mov_b32_e32 v0, s27

; template <int MODE>
; DI void attn_mfma(const Params& p, int l, int b, int hd, int qb, unsigned char* smem) {
;     ...
;   const int tq = qb * QPB + (MODE ? wv : (wv & 1)) * 32 + r;
;   const size_t qrow = (size_t)b * NTOK + tq;
;   bf16x8 qf[KS];
; #pragma unroll
;   for (int ks = 0; ks < KS; ++ks) qf[ks] = *(const bf16x8*)(P + qrow * PW + qcol + (2 * (mp * 2 + ks) + h2) * 8);
;   const bool isctx = qb * QPB < NCTX;
;   int ntiles, band_lo = 0;
;   if (MODE == 0) ntiles = isctx ? 4 : 36;
;   else {
;     if (isctx) ntiles = 4;
;     else { const int i0 = qb * QPB - NCTX; int lo = i0 - 128; if (lo < 0) lo = 0; int hi = i0 + 256; if (hi > NLAT) hi = NLAT; band_lo = lo; ntiles = 4 + (hi - lo) / 64; }
;   }
;   const float cexp = (MODE ? 0.125f : 0.17677669529663687f) * 1.4426950408889634f;
;   float mrun = MODE ? p.sw_sink[l * 4 + hd] * 1.4426950408889634f : -1e30f;
;   float lsum = (MODE && h2 == 0) ? 1.f : 0.f;
;   f32x16 O[2];
; #pragma unroll
;   for (int vt = 0; vt < 2; ++vt)
; #pragma unroll
;     for (int i = 0; i < 16; ++i) O[vt][i] = 0.f;
;   const int lrow = tid >> 3, lc = tid & 7;
; DI void ph_mixers2(const Params& p_in, int l, unsigned char* smem, volatile lds_int* slot) {
;     ...
;     if (it < 512) {
;       int r = it; const int mx = r >> 8; r &= 255;
;       const int sc = 1 + (r & 7); r >>= 3; const int h = r & 3, b = r >> 2;
;       if (mx == 0) rec_output<0>(p, l, b, h, sc, smem); else rec_output<1>(p, l, b, h, sc, smem);
;     } else { const int r = it - 512; const int qb = r % 18, bh = r / 18; if (!(l == 1 && qb < 2)) attn_mfma<1>(p, l, bh >> 2, bh & 3, qb, smem); }
.Lx_attnC:
	s_mov_b64 s[14:15], s[68:69]
	s_cmpk_gt_i32 s27, 0x1ff
	s_cbranch_scc0 .LBB0_831
	s_add_i32 s0, s27, 0xfe00
	s_and_b32 s1, s0, 0xffff
	s_mul_i32 s1, s1, 0xe38f
	s_lshr_b32 s2, s1, 20
	s_mul_i32 s1, s2, 18
	s_sub_i32 s6, s0, s1
	s_and_b32 s0, s6, 0xffff
	s_cmp_lt_u32 s0, 2
	v_readlane_b32 s0, v254, 12
	s_cselect_b64 s[4:5], -1, 0
	v_readlane_b32 s1, v254, 13
	s_and_b64 s[0:1], s[0:1], s[4:5]
	s_and_b64 vcc, exec, s[0:1]
	s_cbranch_vccnz .LBB0_830
	s_add_u32 s0, s14, 0x41c6000
	s_addc_u32 s1, s15, 0
	s_lshl_b32 s6, s6, 7
	s_and_b32 s8, s6, 0xff80
	v_sub_u32_e64 v2, s8, v194 clamp
	s_min_u32 s6, s8, 0x800
	v_readfirstlane_b32 s9, v2
	s_sub_i32 s6, s6, s9
	s_ashr_i32 s6, s6, 6
	s_add_i32 s10, s6, 4
	s_and_b64 s[6:7], s[4:5], exec
	v_mbcnt_lo_u32_b32 v1, -1, 0
	v_mbcnt_hi_u32_b32 v1, -1, v1
	s_cselect_b32 s12, 4, s10
	v_bfe_u32 v0, v1, 5, 1
	v_cmp_eq_u32_e32 vcc, 0, v0
	s_mov_b64 s[6:7], -1
	s_cmp_gt_i32 s12, 0
	s_waitcnt vmcnt(0)
	v_lshlrev_b32_e32 v152, 2, v0
	s_cbranch_scc1 .LBB0_812
	v_mbcnt_hi_u32_b32 v32, -1, v185
	v_and_b32_e32 v2, 64, v32
	v_lshlrev_b32_e32 v35, 2, v0
	v_xor_b32_e32 v33, 32, v32
	v_add_u32_e32 v34, 64, v2
	v_or_b32_e32 v150, 8, v35
	v_or_b32_e32 v148, 16, v35
	v_or_b32_e32 v146, 24, v35
	s_mov_b64 s[6:7], 0
